# Z_H2_E1_D_D2
# baseline (speedup 1.0000x reference)
;     __host__ __device__ bool next(int i, Unit& u) const {
;     ...
;         int wgid = (int)L; { const int q = nwg / NXCD, r = nwg % NXCD, xcd = wgid % NXCD, off = wgid / NXCD; wgid = (xcd < r ? xcd * (q + 1) : r * (q + 1) + (xcd - r) * q) + off; }
;         const int nig = wgm * nN, gid = wgid / nig, fm = gid * wgm, gsz = (nM - fm) < wgm ? (nM - fm) : wgm;
;         u.pm = fm + ((wgid % nig) % gsz); u.pn = (wgid % nig) / gsz; u.sub = 0; return true;
;     __device__ bool next(int i, Unit& u) const { if (!base.next(i >> 1, u)) return false; u.sub = i & 1; return true; }
.LBB0_803:
	s_ashr_i32 s18, s47, 3
	s_add_i32 s18, s51, s18
	s_ashr_i32 s19, s18, 31
	s_lshr_b32 s19, s19, 27
	s_add_i32 s19, s18, s19
	s_ashr_i32 s47, s19, 5
	s_lshl_b32 s47, s47, 2
	s_sub_i32 s50, 0x80, s47
	s_min_i32 s50, s50, 4
	s_andn2_b32 s19, s19, 31
	s_sub_i32 s18, s18, s19
	s_cmp_eq_u32 s50, 4
	s_cselect_b32 s51, 2, 0
	s_lshr_b32 s64, s18, s51
	s_mul_i32 s19, s64, s50
	s_sub_i32 s18, s18, s19
	s_add_i32 s66, s47, s18
	s_and_b32 s47, s46, 1

;     __host__ __device__ bool next(int i, Unit& u) const {
;     ...
;         int wgid = (int)L; { const int q = nwg / NXCD, r = nwg % NXCD, xcd = wgid % NXCD, off = wgid / NXCD; wgid = (xcd < r ? xcd * (q + 1) : r * (q + 1) + (xcd - r) * q) + off; }
;         const int nig = wgm * nN, gid = wgid / nig, fm = gid * wgm, gsz = (nM - fm) < wgm ? (nM - fm) : wgm;
;         u.pm = fm + ((wgid % nig) % gsz); u.pn = (wgid % nig) / gsz; u.sub = 0; return true;
.LBB0_894:
	s_ashr_i32 s18, s40, 3
	s_add_i32 s18, s60, s18
	s_ashr_i32 s19, s18, 31
	s_lshr_b32 s19, s19, 27
	s_add_i32 s19, s18, s19
	s_ashr_i32 s40, s19, 5
	s_lshl_b32 s41, s40, 2
	s_sub_i32 s40, 0x80, s41
	s_min_i32 s60, s40, 4
	s_andn2_b32 s19, s19, 31
	s_sub_i32 s18, s18, s19
	s_cmp_eq_u32 s60, 4
	s_cselect_b32 s40, 2, 0
	s_lshr_b32 s40, s18, s40
	s_mul_i32 s19, s40, s60
	s_sub_i32 s18, s18, s19
	s_add_i32 s60, s41, s18

;     __host__ __device__ bool next(int i, Unit& u) const {
;     ...
;         int wgid = (int)L; { const int q = nwg / NXCD, r = nwg % NXCD, xcd = wgid % NXCD, off = wgid / NXCD; wgid = (xcd < r ? xcd * (q + 1) : r * (q + 1) + (xcd - r) * q) + off; }
;         const int nig = wgm * nN, gid = wgid / nig, fm = gid * wgm, gsz = (nM - fm) < wgm ? (nM - fm) : wgm;
;         u.pm = fm + ((wgid % nig) % gsz); u.pn = (wgid % nig) / gsz; u.sub = 0; return true;
.LBB0_1187:
	s_ashr_i32 s0, s22, 3
	s_add_i32 s0, s26, s0
	s_ashr_i32 s1, s0, 31
	s_lshr_b32 s1, s1, 27
	s_add_i32 s1, s0, s1
	s_ashr_i32 s22, s1, 5
	s_lshl_b32 s22, s22, 2
	s_sub_i32 s23, 0x80, s22
	s_min_i32 s23, s23, 4
	s_andn2_b32 s1, s1, 31
	s_sub_i32 s0, s0, s1
	s_cmp_eq_u32 s23, 4
	s_cselect_b32 s26, 2, 0
	s_lshr_b32 s42, s0, s26
	s_mul_i32 s1, s42, s23
	s_sub_i32 s0, s0, s1
	s_add_i32 s43, s22, s0
